# final LayerNorm: g/b from LDS copy, 32 row loads issued without the mid-block vmcnt(0), no per-step store drains
# baseline (speedup 1.0000x reference)
; __device__ __forceinline__ float bf_lo(unsigned w) { return __uint_as_float(w << 16); }
; __device__ __forceinline__ float bf_hi(unsigned w) { return __uint_as_float(w & 0xffff0000u); }
; template <int MODE, bool COMB, int NR> ...
;     f32x4 v[NR][8]; float sm[NR];
; #pragma unroll
;     for (int i = 0; i < NR; ++i)
; #pragma unroll
;         for (int j = 0; j < 8; ++j) v[i][j] = zero_src ? (f32x4){0.f, 0.f, 0.f, 0.f} : *(const f32x4*)(sp[i] + 4 * lane + 256 * j);
;     if (COMB) {
;         u32x2 sv[NR][8]; float ra[NR], rb[NR];
; #pragma unroll
;         for (int i = 0; i < NR; ++i)
; #pragma unroll
;             for (int j = 0; j < 8; ++j) sv[i][j] = *(const u32x2*)(sb + (size_t)i * D + 4 * lane + 256 * j);
; #pragma unroll
;         for (int i = 0; i < NR; ++i) { const f32x2 ms = st[i]; ra[i] = ALPHA * ms.y; rb[i] = -ms.x * ra[i]; }
; #pragma unroll
;         for (int j = 0; j < 8; ++j) {
;             const f32x4 pgv = *(const f32x4*)(pg + 4 * lane + 256 * j), pbv = *(const f32x4*)(pb + 4 * lane + 256 * j) * ALPHA;
; #pragma unroll
;             for (int i = 0; i < NR; ++i) { const f32x4 s4 = {bf_lo(sv[i][j].x), bf_hi(sv[i][j].x), bf_lo(sv[i][j].y), bf_hi(sv[i][j].y)};
;                 v[i][j] = (v[i][j] * ra[i] + rb[i]) * pgv + pbv + s4 * scale;
;                 if (MODE == 0) *(f32x4*)(dstf + (size_t)i * D + 4 * lane + 256 * j) = v[i][j]; }
;         }
;     }
; #pragma unroll
;     for (int i = 0; i < NR; ++i) { float s = 0.f;
; #pragma unroll
;         for (int j = 0; j < 8; ++j) s += (v[i][j].x + v[i][j].y) + (v[i][j].z + v[i][j].w);
;         sm[i] = s; }
; template <int MODE>
; __device__ __forceinline__ void ln_phase(const Args& a, const float* g, const float* b, int nrows, float scale) {
;     ...
;     if (MODE == 2) {
;         for (int r = 4 * gw; r < NTOK; r += 4 * NGW) { float* x = a.out + (size_t)r * D; const float* const sp[4] = {x, x + D, x + 2 * D, x + 3 * D};
;             ln_rows<2, false, 4>(sp, false, x, nullptr, st, g, b, lane, nullptr, nullptr, nullptr, 0.f); }
.LBB0_451:
	s_and_b64 vcc, exec, s[0:1]
	s_cbranch_vccz .LBB0_456
	v_mov_b32_e32 v2, v155
	s_mov_b32 s0, s22
	v_ashrrev_i32_e32 v1, 4, v2
	v_and_b32_e32 v1, -4, v1
	v_lshl_add_u32 v130, s0, 5, v1
	s_mov_b32 s0, 0xc000
	v_cmp_gt_i32_e32 vcc, s0, v130
	v_readlane_b32 s0, v253, 45
	v_readlane_b32 s1, v253, 46
	v_readlane_b32 s4, v253, 43
	v_readlane_b32 s5, v253, 44
	v_lshlrev_b32_e32 v1, 4, v155
	s_nop 4
	global_load_dwordx4 v[6:9], v1, s[0:1]
	global_load_dwordx4 v[14:17], v1, s[4:5]
	v_add_u32_e32 v1, 0x20000, v1
	s_waitcnt vmcnt(0)
	ds_write_b128 v1, v[6:9]
	ds_write_b128 v1, v[14:17] offset:8192
	s_waitcnt lgkmcnt(0)
	s_barrier
	s_and_saveexec_b64 s[2:3], vcc
	v_readlane_b32 s4, v253, 55
	v_readlane_b32 s5, v253, 56
	s_movk_i32 s6, 0x6000
	s_mov_b32 s8, 0x3727c5ac
	s_cbranch_execz .LBB0_455
	v_xor_b32_e32 v1, 1, v201
	v_cmp_lt_i32_e32 vcc, v1, v202
	v_xor_b32_e32 v3, 2, v201
	v_readlane_b32 s0, v253, 45
	v_cndmask_b32_e32 v1, v201, v1, vcc
	v_cmp_lt_i32_e32 vcc, v3, v202
	v_mov_b32_e32 v5, v0
	v_readlane_b32 s1, v253, 46
	v_cndmask_b32_e32 v3, v201, v3, vcc
	v_lshlrev_b32_e32 v181, 2, v3
	v_xor_b32_e32 v3, 4, v201
	v_cmp_lt_i32_e32 vcc, v3, v202
	v_ashrrev_i32_e32 v131, 31, v130
	v_readlane_b32 s40, v253, 58
	v_cndmask_b32_e32 v3, v201, v3, vcc
	v_lshlrev_b32_e32 v185, 2, v3
	v_xor_b32_e32 v3, 8, v201
	v_cmp_lt_i32_e32 vcc, v3, v202
	v_readlane_b32 s44, v253, 62
	v_readlane_b32 s45, v253, 63
	v_cndmask_b32_e32 v3, v201, v3, vcc
	v_lshlrev_b32_e32 v186, 2, v3
	v_xor_b32_e32 v3, 16, v201
	v_cmp_lt_i32_e32 vcc, v3, v202
	v_lshlrev_b32_e32 v1, 2, v1
	s_mov_b64 s[12:13], 0
	v_cndmask_b32_e32 v3, v201, v3, vcc
	v_lshlrev_b32_e32 v187, 2, v3
	v_xor_b32_e32 v3, 32, v201
	v_cmp_lt_i32_e32 vcc, v3, v202
	v_readlane_b32 s41, v253, 59
	v_readlane_b32 s42, v253, 60
	v_cndmask_b32_e32 v3, v201, v3, vcc
	v_lshlrev_b32_e32 v188, 2, v3
	v_lshlrev_b32_e32 v3, 4, v2
	v_and_b32_e32 v4, 0x3f0, v3
	v_add_u32_e32 v132, 0x20000, v4
	v_readlane_b32 s0, v253, 43
	v_readlane_b32 s1, v253, 44
	v_and_b32_e32 v2, 63, v2
	v_readlane_b32 s43, v253, 61
	s_mov_b64 s[0:1], 0x1000
	s_mov_b64 s[0:1], 0x1400
	s_mov_b64 s[0:1], 0x1800
	v_lshlrev_b64 v[4:5], 13, v[130:131]
	s_mov_b64 s[0:1], 0x1c00
	v_lshl_or_b32 v4, v2, 4, v4
	v_lshl_add_u64 v[152:153], s[44:45], 0, v[4:5]
	v_readlane_b32 s46, v254, 0
	v_readlane_b32 s47, v254, 1
.LBB0_454:
	global_load_dwordx4 v[114:117], v[152:153], off
	global_load_dwordx4 v[102:105], v[152:153], off offset:1024
	global_load_dwordx4 v[78:81], v[152:153], off offset:2048
	global_load_dwordx4 v[58:61], v[152:153], off offset:3072
	v_add_co_u32_e32 v160, vcc, 0x1000, v152
	v_add_u32_e32 v130, s50, v130
	s_nop 0
	v_addc_co_u32_e32 v161, vcc, 0, v153, vcc
	global_load_dwordx4 v[42:45], v[160:161], off
	global_load_dwordx4 v[22:25], v[160:161], off offset:1024
	global_load_dwordx4 v[10:13], v[160:161], off offset:2048
	global_load_dwordx4 v[2:5], v[160:161], off offset:3072
	v_add_co_u32_e32 v168, vcc, 0x2000, v152
	v_addc_co_u32_e32 v169, vcc, 0, v153, vcc
	global_load_dwordx4 v[118:121], v[168:169], off
	global_load_dwordx4 v[106:109], v[168:169], off offset:1024
	global_load_dwordx4 v[82:85], v[168:169], off offset:2048
	global_load_dwordx4 v[66:69], v[168:169], off offset:3072
	v_add_co_u32_e32 v162, vcc, 0x3000, v152
	s_nop 0
	v_addc_co_u32_e32 v163, vcc, 0, v153, vcc
	global_load_dwordx4 v[50:53], v[162:163], off
	global_load_dwordx4 v[34:37], v[162:163], off offset:1024
	global_load_dwordx4 v[18:21], v[162:163], off offset:2048
	global_load_dwordx4 v[6:9], v[162:163], off offset:3072
	v_add_co_u32_e32 v170, vcc, s79, v152
	s_nop 0
	v_addc_co_u32_e32 v171, vcc, 0, v153, vcc
	global_load_dwordx4 v[122:125], v[170:171], off
	global_load_dwordx4 v[98:101], v[170:171], off offset:1024
	global_load_dwordx4 v[90:93], v[170:171], off offset:2048
	global_load_dwordx4 v[70:73], v[170:171], off offset:3072
	v_add_co_u32_e32 v164, vcc, 0x5000, v152
	s_nop 0
	v_addc_co_u32_e32 v165, vcc, 0, v153, vcc
	global_load_dwordx4 v[62:65], v[164:165], off
	global_load_dwordx4 v[46:49], v[164:165], off offset:1024
	global_load_dwordx4 v[26:29], v[164:165], off offset:2048
	global_load_dwordx4 v[14:17], v[164:165], off offset:3072
	v_add_co_u32_e32 v172, vcc, s6, v152
	s_nop 0
	v_addc_co_u32_e32 v173, vcc, 0, v153, vcc
	global_load_dwordx4 v[126:129], v[172:173], off
	global_load_dwordx4 v[110:113], v[172:173], off offset:1024
	global_load_dwordx4 v[94:97], v[172:173], off offset:2048
	global_load_dwordx4 v[86:89], v[172:173], off offset:3072
	v_add_co_u32_e32 v166, vcc, 0x7000, v152
	s_nop 0
	v_addc_co_u32_e32 v167, vcc, 0, v153, vcc
	global_load_dwordx4 v[74:77], v[166:167], off
	global_load_dwordx4 v[54:57], v[166:167], off offset:1024
	global_load_dwordx4 v[38:41], v[166:167], off offset:2048
	global_load_dwordx4 v[30:33], v[166:167], off offset:3072
	s_waitcnt vmcnt(24)
	v_mov_b32_e32 v174, v114
	v_mov_b32_e32 v175, v102
	v_mov_b32_e32 v176, v115
	v_mov_b32_e32 v177, v103
	v_pk_add_f32 v[174:175], v[174:175], v[176:177]
	v_mov_b32_e32 v176, v116
	v_mov_b32_e32 v177, v104
	v_mov_b32_e32 v178, v117
	v_mov_b32_e32 v179, v105
	v_pk_add_f32 v[176:177], v[176:177], v[178:179]
	v_mov_b32_e32 v178, v78
	v_pk_add_f32 v[174:175], v[174:175], v[176:177]
	v_mov_b32_e32 v176, v79
	v_mov_b32_e32 v177, v80
	v_mov_b32_e32 v179, v81
	v_pk_add_f32 v[176:177], v[176:177], v[178:179]
	v_add_f32_e32 v131, 0, v174
	v_pk_add_f32 v[176:177], v[176:177], v[176:177] op_sel:[0,1] op_sel_hi:[1,0]
	v_add_f32_e32 v174, v131, v175
	v_add_f32_e32 v178, v58, v59
	v_add_f32_e32 v182, v60, v61
	v_mov_b32_e32 v175, v42
	v_mov_b32_e32 v177, v43
	v_mov_b32_e32 v179, v44
	v_mov_b32_e32 v183, v45
	v_pk_add_f32 v[174:175], v[174:175], v[176:177]
	v_pk_add_f32 v[176:177], v[178:179], v[182:183]
	v_mov_b32_e32 v178, v22
	v_pk_add_f32 v[174:175], v[174:175], v[176:177]
	v_mov_b32_e32 v176, v23
	v_mov_b32_e32 v177, v24
	v_mov_b32_e32 v179, v25
	v_pk_add_f32 v[176:177], v[176:177], v[178:179]
	v_pk_add_f32 v[174:175], v[174:175], v[174:175] op_sel:[0,1] op_sel_hi:[1,0]
	v_pk_add_f32 v[176:177], v[176:177], v[176:177] op_sel:[0,1] op_sel_hi:[1,0]
	v_add_f32_e32 v178, v10, v11
	v_add_f32_e32 v182, v12, v13
	v_mov_b32_e32 v175, v2
	v_mov_b32_e32 v177, v3
	v_mov_b32_e32 v179, v4
	v_mov_b32_e32 v183, v5
	v_pk_add_f32 v[174:175], v[174:175], v[176:177]
	v_pk_add_f32 v[176:177], v[178:179], v[182:183]
	s_waitcnt vmcnt(23)
; template <int MODE, bool COMB, int NR> ...
;     ...
; #pragma unroll
;     for (int i = 0; i < NR; ++i) { float s = 0.f;
; #pragma unroll
;         for (int j = 0; j < 8; ++j) s += (v[i][j].x + v[i][j].y) + (v[i][j].z + v[i][j].w);
;         sm[i] = s; }
;     if (MODE == 1) {
; #pragma unroll
;         for (int i = 0; i < NR; ++i)
; #pragma unroll
;             for (int j = 0; j < 8; ++j) *(f32x4*)(dstf + (size_t)i * D + 4 * lane + 256 * j) = v[i][j];
;     }
; #pragma unroll
;     for (int o = 1; o < 64; o <<= 1) {
; #pragma unroll
;         for (int i = 0; i < NR; ++i) sm[i] += __shfl_xor(sm[i], o); }
	v_mov_b32_e32 v178, v121
	v_pk_add_f32 v[174:175], v[174:175], v[176:177]
	v_mov_b32_e32 v176, v119
	v_add_f32_e32 v131, v174, v175
	v_mov_b32_e32 v174, v118
	s_waitcnt vmcnt(22)
	v_mov_b32_e32 v175, v106
	v_mov_b32_e32 v177, v107
	v_pk_add_f32 v[174:175], v[174:175], v[176:177]
	v_mov_b32_e32 v176, v120
	v_mov_b32_e32 v177, v108
	v_mov_b32_e32 v179, v109
	v_pk_add_f32 v[176:177], v[176:177], v[178:179]
	s_waitcnt vmcnt(21)
	v_mov_b32_e32 v178, v82
	v_pk_add_f32 v[174:175], v[174:175], v[176:177]
	v_mov_b32_e32 v176, v83
	v_mov_b32_e32 v177, v84
	v_mov_b32_e32 v179, v85
	v_pk_add_f32 v[176:177], v[176:177], v[178:179]
	v_add_f32_e32 v174, 0, v174
	v_pk_add_f32 v[176:177], v[176:177], v[176:177] op_sel:[0,1] op_sel_hi:[1,0]
	v_add_f32_e32 v174, v174, v175
	s_waitcnt vmcnt(20)
	v_add_f32_e32 v178, v66, v67
	v_add_f32_e32 v182, v68, v69
	s_waitcnt vmcnt(19)
	v_mov_b32_e32 v175, v50
	v_mov_b32_e32 v177, v51
	v_mov_b32_e32 v179, v52
	v_mov_b32_e32 v183, v53
	v_pk_add_f32 v[174:175], v[174:175], v[176:177]
	v_pk_add_f32 v[176:177], v[178:179], v[182:183]
	s_waitcnt vmcnt(18)
	v_mov_b32_e32 v178, v34
	v_pk_add_f32 v[174:175], v[174:175], v[176:177]
	v_mov_b32_e32 v176, v35
	v_mov_b32_e32 v177, v36
	v_mov_b32_e32 v179, v37
	v_pk_add_f32 v[176:177], v[176:177], v[178:179]
	v_pk_add_f32 v[174:175], v[174:175], v[174:175] op_sel:[0,1] op_sel_hi:[1,0]
	v_pk_add_f32 v[176:177], v[176:177], v[176:177] op_sel:[0,1] op_sel_hi:[1,0]
	s_waitcnt vmcnt(17)
	v_add_f32_e32 v178, v18, v19
	v_add_f32_e32 v182, v20, v21
	s_waitcnt vmcnt(16)
	v_mov_b32_e32 v175, v6
	v_mov_b32_e32 v177, v7
	v_mov_b32_e32 v179, v8
	v_mov_b32_e32 v183, v9
	v_pk_add_f32 v[174:175], v[174:175], v[176:177]
	v_pk_add_f32 v[176:177], v[178:179], v[182:183]
	s_waitcnt vmcnt(15)
	v_mov_b32_e32 v178, v123
	v_pk_add_f32 v[174:175], v[174:175], v[176:177]
	v_mov_b32_e32 v176, v122
	s_waitcnt vmcnt(14)
	v_mov_b32_e32 v177, v98
	v_mov_b32_e32 v179, v99
	v_pk_add_f32 v[176:177], v[176:177], v[178:179]
	v_mov_b32_e32 v178, v124
	v_mov_b32_e32 v179, v100
	v_mov_b32_e32 v182, v125
	v_mov_b32_e32 v183, v101
	v_pk_add_f32 v[178:179], v[178:179], v[182:183]
	s_waitcnt vmcnt(13)
	v_mov_b32_e32 v182, v90
	v_pk_add_f32 v[176:177], v[176:177], v[178:179]
	v_mov_b32_e32 v178, v91
	v_mov_b32_e32 v179, v92
	v_mov_b32_e32 v183, v93
	v_pk_add_f32 v[178:179], v[178:179], v[182:183]
	v_add_f32_e32 v174, v174, v175
	v_add_f32_e32 v175, 0, v176
	v_pk_add_f32 v[178:179], v[178:179], v[178:179] op_sel:[0,1] op_sel_hi:[1,0]
	v_add_f32_e32 v176, v175, v177
	s_waitcnt vmcnt(12)
	v_add_f32_e32 v182, v70, v71
	v_add_f32_e32 v190, v72, v73
	s_waitcnt vmcnt(11)
	v_mov_b32_e32 v177, v62
	v_mov_b32_e32 v179, v63
	v_mov_b32_e32 v183, v64
	v_mov_b32_e32 v191, v65
	v_pk_add_f32 v[176:177], v[176:177], v[178:179]
	v_pk_add_f32 v[178:179], v[182:183], v[190:191]
	s_waitcnt vmcnt(10)
	v_mov_b32_e32 v182, v46
	v_pk_add_f32 v[176:177], v[176:177], v[178:179]
	v_mov_b32_e32 v178, v47
	v_mov_b32_e32 v179, v48
	v_mov_b32_e32 v183, v49
	v_pk_add_f32 v[178:179], v[178:179], v[182:183]
	v_pk_add_f32 v[176:177], v[176:177], v[176:177] op_sel:[0,1] op_sel_hi:[1,0]
	v_pk_add_f32 v[178:179], v[178:179], v[178:179] op_sel:[0,1] op_sel_hi:[1,0]
	s_waitcnt vmcnt(9)
	v_add_f32_e32 v182, v26, v27
	v_add_f32_e32 v190, v28, v29
	s_waitcnt vmcnt(8)
	v_mov_b32_e32 v177, v14
	v_mov_b32_e32 v179, v15
	v_mov_b32_e32 v183, v16
	v_mov_b32_e32 v191, v17
	v_pk_add_f32 v[176:177], v[176:177], v[178:179]
	v_pk_add_f32 v[178:179], v[182:183], v[190:191]
	s_waitcnt vmcnt(7)
	v_mov_b32_e32 v182, v129
	v_pk_add_f32 v[176:177], v[176:177], v[178:179]
	v_mov_b32_e32 v178, v127
	v_add_f32_e32 v175, v176, v177
	v_mov_b32_e32 v176, v126
	s_waitcnt vmcnt(6)
	v_mov_b32_e32 v177, v110
	v_mov_b32_e32 v179, v111
	v_pk_add_f32 v[176:177], v[176:177], v[178:179]
	v_mov_b32_e32 v178, v128
	v_mov_b32_e32 v179, v112
	v_mov_b32_e32 v183, v113
	v_pk_add_f32 v[178:179], v[178:179], v[182:183]
	s_waitcnt vmcnt(5)
	v_mov_b32_e32 v182, v94
	v_pk_add_f32 v[176:177], v[176:177], v[178:179]
	v_mov_b32_e32 v178, v95
	v_mov_b32_e32 v179, v96
	v_mov_b32_e32 v183, v97
	v_pk_add_f32 v[178:179], v[178:179], v[182:183]
	v_add_f32_e32 v176, 0, v176
	v_pk_add_f32 v[178:179], v[178:179], v[178:179] op_sel:[0,1] op_sel_hi:[1,0]
	v_add_f32_e32 v176, v176, v177
	s_waitcnt vmcnt(4)
	v_add_f32_e32 v182, v86, v87
	v_add_f32_e32 v190, v88, v89
	s_waitcnt vmcnt(3)
	v_mov_b32_e32 v177, v74
	v_mov_b32_e32 v179, v75
	v_mov_b32_e32 v183, v76
	v_mov_b32_e32 v191, v77
	v_pk_add_f32 v[176:177], v[176:177], v[178:179]
	v_pk_add_f32 v[178:179], v[182:183], v[190:191]
	s_waitcnt vmcnt(2)
	v_mov_b32_e32 v182, v54
	v_pk_add_f32 v[176:177], v[176:177], v[178:179]
	v_mov_b32_e32 v178, v55
	v_mov_b32_e32 v179, v56
	v_mov_b32_e32 v183, v57
	v_pk_add_f32 v[178:179], v[178:179], v[182:183]
	v_pk_add_f32 v[176:177], v[176:177], v[176:177] op_sel:[0,1] op_sel_hi:[1,0]
	v_pk_add_f32 v[178:179], v[178:179], v[178:179] op_sel:[0,1] op_sel_hi:[1,0]
	s_waitcnt vmcnt(1)
	v_add_f32_e32 v182, v38, v39
	v_add_f32_e32 v190, v40, v41
	s_waitcnt vmcnt(0)
	v_mov_b32_e32 v177, v30
	v_mov_b32_e32 v179, v31
	v_mov_b32_e32 v183, v32
	v_mov_b32_e32 v191, v33
	v_pk_add_f32 v[176:177], v[176:177], v[178:179]
	v_pk_add_f32 v[178:179], v[182:183], v[190:191]
	s_nop 0
	v_pk_add_f32 v[176:177], v[176:177], v[178:179]
	s_nop 0
	v_add_f32_e32 v176, v176, v177
	ds_bpermute_b32 v177, v1, v131
	s_waitcnt lgkmcnt(0)
	v_add_f32_e32 v131, v131, v177
	ds_bpermute_b32 v177, v1, v174
	s_waitcnt lgkmcnt(0)
	v_add_f32_e32 v174, v174, v177
	ds_bpermute_b32 v177, v1, v175
	s_waitcnt lgkmcnt(0)
	v_add_f32_e32 v175, v175, v177
	ds_bpermute_b32 v177, v1, v176
	s_waitcnt lgkmcnt(0)
; template <int MODE, bool COMB, int NR> ...
;     ...
; #pragma unroll
;     for (int o = 1; o < 64; o <<= 1) {
; #pragma unroll
;         for (int i = 0; i < NR; ++i) sm[i] += __shfl_xor(sm[i], o); }
;     float mean[NR], q[NR], rstd[NR];
; #pragma unroll
;     for (int i = 0; i < NR; ++i) { mean[i] = sm[i] * (1.f / D); float s2 = 0.f;
; #pragma unroll
;         for (int j = 0; j < 8; ++j) { v[i][j] = v[i][j] - mean[i]; s2 += (v[i][j].x * v[i][j].x + v[i][j].y * v[i][j].y) + (v[i][j].z * v[i][j].z + v[i][j].w * v[i][j].w); }
;         q[i] = s2; }
	v_add_f32_e32 v176, v176, v177
	ds_bpermute_b32 v177, v181, v131
	s_waitcnt lgkmcnt(0)
	v_add_f32_e32 v131, v131, v177
	ds_bpermute_b32 v177, v181, v174
	s_waitcnt lgkmcnt(0)
	v_add_f32_e32 v174, v174, v177
	ds_bpermute_b32 v177, v181, v175
	s_waitcnt lgkmcnt(0)
	v_add_f32_e32 v175, v175, v177
	ds_bpermute_b32 v177, v181, v176
	s_waitcnt lgkmcnt(0)
	v_add_f32_e32 v176, v176, v177
	ds_bpermute_b32 v177, v185, v131
	s_waitcnt lgkmcnt(0)
	v_add_f32_e32 v131, v131, v177
	ds_bpermute_b32 v177, v185, v174
	s_waitcnt lgkmcnt(0)
	v_add_f32_e32 v174, v174, v177
	ds_bpermute_b32 v177, v185, v175
	s_waitcnt lgkmcnt(0)
	v_add_f32_e32 v175, v175, v177
	ds_bpermute_b32 v177, v185, v176
	s_waitcnt lgkmcnt(0)
	v_add_f32_e32 v176, v176, v177
	ds_bpermute_b32 v177, v186, v131
	s_waitcnt lgkmcnt(0)
	v_add_f32_e32 v131, v131, v177
	ds_bpermute_b32 v177, v186, v174
	s_waitcnt lgkmcnt(0)
	v_add_f32_e32 v174, v174, v177
	ds_bpermute_b32 v177, v186, v175
	s_waitcnt lgkmcnt(0)
	v_add_f32_e32 v175, v175, v177
	ds_bpermute_b32 v177, v186, v176
	s_waitcnt lgkmcnt(0)
	v_add_f32_e32 v176, v176, v177
	ds_bpermute_b32 v177, v187, v131
	s_waitcnt lgkmcnt(0)
	v_add_f32_e32 v131, v131, v177
	ds_bpermute_b32 v177, v187, v174
	s_waitcnt lgkmcnt(0)
	v_add_f32_e32 v174, v174, v177
	ds_bpermute_b32 v177, v187, v175
	s_waitcnt lgkmcnt(0)
	v_add_f32_e32 v175, v175, v177
	ds_bpermute_b32 v177, v187, v176
	s_waitcnt lgkmcnt(0)
	v_add_f32_e32 v176, v176, v177
	ds_bpermute_b32 v177, v188, v131
	s_waitcnt lgkmcnt(0)
	v_add_f32_e32 v183, v131, v177
	ds_bpermute_b32 v131, v188, v174
	v_fmamk_f32 v115, v183, 0xba000000, v115
	v_fmamk_f32 v103, v183, 0xba000000, v103
	v_fmac_f32_e32 v114, 0xba000000, v183
	v_fmac_f32_e32 v102, 0xba000000, v183
	s_waitcnt lgkmcnt(0)
	v_add_f32_e32 v182, v174, v131
	ds_bpermute_b32 v131, v188, v175
	v_mov_b32_e32 v177, v103
	v_fmamk_f32 v174, v183, 0xba000000, v116
	v_fmamk_f32 v116, v183, 0xba000000, v104
	v_mov_b32_e32 v104, v114
	s_waitcnt lgkmcnt(0)
	v_add_f32_e32 v180, v175, v131
	ds_bpermute_b32 v131, v188, v176
	v_fmamk_f32 v175, v183, 0xba000000, v117
	v_fmamk_f32 v117, v183, 0xba000000, v105
	v_mov_b32_e32 v105, v102
	v_mov_b32_e32 v178, v175
	s_waitcnt lgkmcnt(0)
	v_add_f32_e32 v131, v176, v131
	v_mov_b32_e32 v176, v115
	v_pk_mul_f32 v[176:177], v[176:177], v[176:177]
	v_mov_b32_e32 v179, v117
	v_pk_fma_f32 v[104:105], v[104:105], v[104:105], v[176:177]
	v_mov_b32_e32 v176, v174
	v_mov_b32_e32 v177, v116
	v_pk_mul_f32 v[178:179], v[178:179], v[178:179]
	v_fmamk_f32 v81, v183, 0xba000000, v81
	v_pk_fma_f32 v[176:177], v[176:177], v[176:177], v[178:179]
	v_fmac_f32_e32 v80, 0xba000000, v183
	v_pk_add_f32 v[104:105], v[104:105], v[176:177]
	v_fmac_f32_e32 v60, 0xba000000, v183
	v_pk_add_f32 v[176:177], v[104:105], v[104:105] op_sel_hi:[0,1]
	v_fmamk_f32 v105, v183, 0xba000000, v79
	v_fmamk_f32 v104, v183, 0xba000000, v78
	v_pk_mul_f32 v[78:79], v[80:81], v[80:81]
	v_pk_mul_f32 v[178:179], v[104:105], v[104:105]
	v_fmamk_f32 v61, v183, 0xba000000, v61
	v_pk_mov_b32 v[190:191], v[178:179], v[78:79] op_sel:[1,0]
	v_mov_b32_e32 v179, v79
	v_pk_add_f32 v[78:79], v[190:191], v[178:179]
	v_fmamk_f32 v43, v183, 0xba000000, v43
	v_pk_add_f32 v[178:179], v[78:79], v[78:79] op_sel_hi:[0,1]
	v_fmamk_f32 v78, v183, 0xba000000, v58
	v_fmamk_f32 v79, v183, 0xba000000, v59
	v_mul_f32_e32 v58, v78, v78
	v_pk_fma_f32 v[190:191], v[78:79], v[78:79], v[58:59] op_sel_hi:[1,1,0]
	v_mul_f32_e32 v58, v60, v60
	v_pk_fma_f32 v[192:193], v[60:61], v[60:61], v[58:59] op_sel_hi:[1,1,0]
	v_fmamk_f32 v59, v183, 0xba000000, v45
	v_fmamk_f32 v58, v183, 0xba000000, v44
	v_fmac_f32_e32 v42, 0xba000000, v183
	v_mul_f32_e32 v190, v42, v42
	v_mul_f32_e32 v192, v43, v43
	v_mul_f32_e32 v178, v58, v58
	v_mul_f32_e32 v176, v59, v59
	v_pk_add_f32 v[44:45], v[190:191], v[192:193]
	v_pk_add_f32 v[176:177], v[178:179], v[176:177]
	v_fmamk_f32 v25, v183, 0xba000000, v25
	v_pk_add_f32 v[44:45], v[44:45], v[176:177]
	v_fmac_f32_e32 v24, 0xba000000, v183
	v_pk_add_f32 v[176:177], v[44:45], v[44:45] op_sel_hi:[0,1]
	v_fmamk_f32 v45, v183, 0xba000000, v23
	v_fmamk_f32 v44, v183, 0xba000000, v22
	v_pk_mul_f32 v[22:23], v[24:25], v[24:25]
	v_pk_mul_f32 v[178:179], v[44:45], v[44:45]
	v_fmac_f32_e32 v12, 0xba000000, v183
	v_pk_mov_b32 v[190:191], v[178:179], v[22:23] op_sel:[1,0]
	v_mov_b32_e32 v179, v23
	v_pk_add_f32 v[22:23], v[190:191], v[178:179]
	v_fmamk_f32 v13, v183, 0xba000000, v13
	v_pk_add_f32 v[178:179], v[22:23], v[22:23] op_sel_hi:[0,1]
	v_fmamk_f32 v22, v183, 0xba000000, v10
	v_fmamk_f32 v23, v183, 0xba000000, v11
	v_mul_f32_e32 v10, v22, v22
	v_pk_fma_f32 v[10:11], v[22:23], v[22:23], v[10:11] op_sel_hi:[1,1,0]
	v_fmamk_f32 v5, v183, 0xba000000, v5
	v_mul_f32_e32 v10, v12, v12
	v_pk_fma_f32 v[190:191], v[12:13], v[12:13], v[10:11] op_sel_hi:[1,1,0]
	v_fmamk_f32 v4, v183, 0xba000000, v4
	v_fmamk_f32 v3, v183, 0xba000000, v3
	v_fmac_f32_e32 v2, 0xba000000, v183
	v_mul_f32_e32 v10, v2, v2
	v_mul_f32_e32 v190, v3, v3
	v_mul_f32_e32 v178, v4, v4
	v_mul_f32_e32 v176, v5, v5
	v_pk_add_f32 v[10:11], v[10:11], v[190:191]
	v_pk_add_f32 v[176:177], v[178:179], v[176:177]
	v_fmamk_f32 v119, v182, 0xba000000, v119
	v_fmamk_f32 v107, v182, 0xba000000, v107
	v_pk_add_f32 v[10:11], v[10:11], v[176:177]
	v_fmamk_f32 v179, v182, 0xba000000, v121
	v_fmamk_f32 v178, v182, 0xba000000, v120
	v_fmac_f32_e32 v118, 0xba000000, v182
	v_fmamk_f32 v177, v182, 0xba000000, v109
	v_fmac_f32_e32 v106, 0xba000000, v182
	v_mov_b32_e32 v120, v119
	v_mov_b32_e32 v121, v107
	v_fmamk_f32 v176, v182, 0xba000000, v108
	v_mov_b32_e32 v108, v118
	v_mov_b32_e32 v109, v106
	v_pk_mul_f32 v[120:121], v[120:121], v[120:121]
; template <int MODE, bool COMB, int NR> ...
;     ...
;     float mean[NR], q[NR], rstd[NR];
; #pragma unroll
;     for (int i = 0; i < NR; ++i) { mean[i] = sm[i] * (1.f / D); float s2 = 0.f;
; #pragma unroll
;         for (int j = 0; j < 8; ++j) { v[i][j] = v[i][j] - mean[i]; s2 += (v[i][j].x * v[i][j].x + v[i][j].y * v[i][j].y) + (v[i][j].z * v[i][j].z + v[i][j].w * v[i][j].w); }
;         q[i] = s2; }
	v_mov_b32_e32 v190, v179
	v_mov_b32_e32 v191, v177
	v_pk_fma_f32 v[108:109], v[108:109], v[108:109], v[120:121]
	v_mov_b32_e32 v120, v178
	v_mov_b32_e32 v121, v176
	v_pk_mul_f32 v[190:191], v[190:191], v[190:191]
	v_fmamk_f32 v85, v182, 0xba000000, v85
	v_pk_fma_f32 v[120:121], v[120:121], v[120:121], v[190:191]
	v_fmac_f32_e32 v84, 0xba000000, v182
	v_pk_add_f32 v[108:109], v[108:109], v[120:121]
	v_fmamk_f32 v121, v182, 0xba000000, v83
	v_fmamk_f32 v120, v182, 0xba000000, v82
	v_pk_add_f32 v[190:191], v[108:109], v[108:109] op_sel_hi:[0,1]
	v_pk_mul_f32 v[82:83], v[84:85], v[84:85]
	v_pk_mul_f32 v[108:109], v[120:121], v[120:121]
	v_fmac_f32_e32 v68, 0xba000000, v182
	v_pk_mov_b32 v[192:193], v[108:109], v[82:83] op_sel:[1,0]
	v_mov_b32_e32 v109, v83
	v_pk_add_f32 v[82:83], v[192:193], v[108:109]
	v_fmamk_f32 v108, v182, 0xba000000, v66
	v_fmamk_f32 v109, v182, 0xba000000, v67
	v_mul_f32_e32 v66, v108, v108
	v_pk_fma_f32 v[66:67], v[108:109], v[108:109], v[66:67] op_sel_hi:[1,1,0]
	v_fmamk_f32 v69, v182, 0xba000000, v69
	v_mul_f32_e32 v66, v68, v68
	v_pk_add_f32 v[192:193], v[82:83], v[82:83] op_sel_hi:[0,1]
	v_pk_fma_f32 v[194:195], v[68:69], v[68:69], v[66:67] op_sel_hi:[1,1,0]
	v_fmamk_f32 v83, v182, 0xba000000, v53
	v_fmamk_f32 v82, v182, 0xba000000, v52
	v_fmamk_f32 v51, v182, 0xba000000, v51
	v_fmac_f32_e32 v50, 0xba000000, v182
	v_mul_f32_e32 v66, v50, v50
	v_mul_f32_e32 v194, v51, v51
	v_mul_f32_e32 v192, v82, v82
	v_mul_f32_e32 v190, v83, v83
	v_pk_add_f32 v[52:53], v[66:67], v[194:195]
	v_pk_add_f32 v[66:67], v[192:193], v[190:191]
	v_fmamk_f32 v37, v182, 0xba000000, v37
	v_pk_add_f32 v[52:53], v[52:53], v[66:67]
	v_fmamk_f32 v67, v182, 0xba000000, v35
	v_fmamk_f32 v66, v182, 0xba000000, v34
	v_fmac_f32_e32 v36, 0xba000000, v182
	v_pk_add_f32 v[190:191], v[52:53], v[52:53] op_sel_hi:[0,1]
	v_pk_mul_f32 v[34:35], v[36:37], v[36:37]
	v_pk_mul_f32 v[52:53], v[66:67], v[66:67]
	v_fmac_f32_e32 v20, 0xba000000, v182
	v_pk_mov_b32 v[192:193], v[52:53], v[34:35] op_sel:[1,0]
	v_mov_b32_e32 v53, v35
	v_pk_add_f32 v[34:35], v[192:193], v[52:53]
	v_fmamk_f32 v52, v182, 0xba000000, v18
	v_fmamk_f32 v53, v182, 0xba000000, v19
	v_mul_f32_e32 v18, v52, v52
	v_pk_fma_f32 v[18:19], v[52:53], v[52:53], v[18:19] op_sel_hi:[1,1,0]
	v_fmamk_f32 v21, v182, 0xba000000, v21
	v_mul_f32_e32 v18, v20, v20
	v_pk_add_f32 v[192:193], v[34:35], v[34:35] op_sel_hi:[0,1]
	v_pk_fma_f32 v[194:195], v[20:21], v[20:21], v[18:19] op_sel_hi:[1,1,0]
	v_fmamk_f32 v35, v182, 0xba000000, v9
	v_fmamk_f32 v34, v182, 0xba000000, v8
	v_fmamk_f32 v7, v182, 0xba000000, v7
	v_fmac_f32_e32 v6, 0xba000000, v182
	v_mul_f32_e32 v18, v6, v6
	v_mul_f32_e32 v194, v7, v7
	v_mul_f32_e32 v192, v34, v34
	v_mul_f32_e32 v190, v35, v35
	v_pk_add_f32 v[8:9], v[18:19], v[194:195]
	v_pk_add_f32 v[18:19], v[192:193], v[190:191]
	v_fmamk_f32 v123, v180, 0xba000000, v123
	v_fmamk_f32 v99, v180, 0xba000000, v99
	v_pk_add_f32 v[8:9], v[8:9], v[18:19]
	v_fmamk_f32 v19, v180, 0xba000000, v125
	v_fmac_f32_e32 v122, 0xba000000, v180
	v_fmamk_f32 v125, v180, 0xba000000, v101
	v_fmac_f32_e32 v98, 0xba000000, v180
	v_mov_b32_e32 v182, v123
	v_mov_b32_e32 v183, v99
	v_fmamk_f32 v18, v180, 0xba000000, v124
	v_fmamk_f32 v124, v180, 0xba000000, v100
	v_mov_b32_e32 v100, v122
	v_mov_b32_e32 v101, v98
	v_pk_mul_f32 v[182:183], v[182:183], v[182:183]
	v_mov_b32_e32 v190, v19
	v_mov_b32_e32 v191, v125
	v_pk_fma_f32 v[100:101], v[100:101], v[100:101], v[182:183]
	v_mov_b32_e32 v182, v18
	v_mov_b32_e32 v183, v124
	v_pk_mul_f32 v[190:191], v[190:191], v[190:191]
	v_fmamk_f32 v93, v180, 0xba000000, v93
	v_pk_fma_f32 v[182:183], v[182:183], v[182:183], v[190:191]
	v_fmac_f32_e32 v92, 0xba000000, v180
	v_pk_add_f32 v[100:101], v[100:101], v[182:183]
	v_fmac_f32_e32 v72, 0xba000000, v180
	v_pk_add_f32 v[182:183], v[100:101], v[100:101] op_sel_hi:[0,1]
	v_fmamk_f32 v101, v180, 0xba000000, v91
	v_fmamk_f32 v100, v180, 0xba000000, v90
	v_pk_mul_f32 v[90:91], v[92:93], v[92:93]
	v_pk_mul_f32 v[190:191], v[100:101], v[100:101]
	v_fmamk_f32 v73, v180, 0xba000000, v73
	v_pk_mov_b32 v[192:193], v[190:191], v[90:91] op_sel:[1,0]
	v_mov_b32_e32 v191, v91
	v_pk_add_f32 v[90:91], v[192:193], v[190:191]
	v_fmamk_f32 v63, v180, 0xba000000, v63
	v_pk_add_f32 v[190:191], v[90:91], v[90:91] op_sel_hi:[0,1]
	v_fmamk_f32 v90, v180, 0xba000000, v70
	v_fmamk_f32 v91, v180, 0xba000000, v71
	v_mul_f32_e32 v70, v90, v90
	v_pk_fma_f32 v[192:193], v[90:91], v[90:91], v[70:71] op_sel_hi:[1,1,0]
	v_mul_f32_e32 v70, v72, v72
	v_pk_fma_f32 v[194:195], v[72:73], v[72:73], v[70:71] op_sel_hi:[1,1,0]
	v_fmamk_f32 v71, v180, 0xba000000, v65
	v_fmamk_f32 v70, v180, 0xba000000, v64
	v_fmac_f32_e32 v62, 0xba000000, v180
	v_mul_f32_e32 v192, v62, v62
	v_mul_f32_e32 v194, v63, v63
	v_mul_f32_e32 v190, v70, v70
	v_mul_f32_e32 v182, v71, v71
	v_pk_add_f32 v[64:65], v[192:193], v[194:195]
	v_pk_add_f32 v[182:183], v[190:191], v[182:183]
	v_fmamk_f32 v49, v180, 0xba000000, v49
	v_pk_add_f32 v[64:65], v[64:65], v[182:183]
	v_fmac_f32_e32 v48, 0xba000000, v180
	v_pk_add_f32 v[182:183], v[64:65], v[64:65] op_sel_hi:[0,1]
	v_fmamk_f32 v65, v180, 0xba000000, v47
	v_fmamk_f32 v64, v180, 0xba000000, v46
	v_pk_mul_f32 v[46:47], v[48:49], v[48:49]
	v_pk_mul_f32 v[190:191], v[64:65], v[64:65]
	v_fmac_f32_e32 v28, 0xba000000, v180
	v_pk_mov_b32 v[192:193], v[190:191], v[46:47] op_sel:[1,0]
	v_mov_b32_e32 v191, v47
	v_pk_add_f32 v[46:47], v[192:193], v[190:191]
	v_fmamk_f32 v29, v180, 0xba000000, v29
	v_pk_add_f32 v[190:191], v[46:47], v[46:47] op_sel_hi:[0,1]
	v_fmamk_f32 v46, v180, 0xba000000, v26
	v_fmamk_f32 v47, v180, 0xba000000, v27
	v_mul_f32_e32 v26, v46, v46
; template <int MODE, bool COMB, int NR> ...
;     ...
;     float mean[NR], q[NR], rstd[NR];
; #pragma unroll
;     for (int i = 0; i < NR; ++i) { mean[i] = sm[i] * (1.f / D); float s2 = 0.f;
; #pragma unroll
;         for (int j = 0; j < 8; ++j) { v[i][j] = v[i][j] - mean[i]; s2 += (v[i][j].x * v[i][j].x + v[i][j].y * v[i][j].y) + (v[i][j].z * v[i][j].z + v[i][j].w * v[i][j].w); }
;         q[i] = s2; }
; #pragma unroll
;     for (int o = 1; o < 64; o <<= 1) {
; #pragma unroll
;         for (int i = 0; i < NR; ++i) q[i] += __shfl_xor(q[i], o); }
; #pragma unroll
;     for (int i = 0; i < NR; ++i) rstd[i] = rsqrtf(q[i] * (1.f / D) + LN_EPS);
;     if (MODE != 2) {
; #pragma unroll
;         for (int i = 0; i < NR; ++i) if (lane == i) st[i] = (f32x2){mean[i], rstd[i]};
;     }
; #pragma unroll
;     for (int j = 0; j < 8; ++j) {
;         const f32x4 gg = *(const f32x4*)(g + 4 * lane + 256 * j), bb = *(const f32x4*)(b + 4 * lane + 256 * j);
; #pragma unroll
;         for (int i = 0; i < NR; ++i) {
;             const f32x4 y = v[i][j] * rstd[i] * gg + bb;
	v_pk_fma_f32 v[192:193], v[46:47], v[46:47], v[26:27] op_sel_hi:[1,1,0]
	v_mul_f32_e32 v26, v28, v28
	v_pk_fma_f32 v[194:195], v[28:29], v[28:29], v[26:27] op_sel_hi:[1,1,0]
	v_fmamk_f32 v27, v180, 0xba000000, v17
	v_fmamk_f32 v26, v180, 0xba000000, v16
	v_fmamk_f32 v15, v180, 0xba000000, v15
	v_fmac_f32_e32 v14, 0xba000000, v180
	v_mul_f32_e32 v192, v14, v14
	v_mul_f32_e32 v194, v15, v15
	v_mul_f32_e32 v190, v26, v26
	v_mul_f32_e32 v182, v27, v27
	v_pk_add_f32 v[16:17], v[192:193], v[194:195]
	v_pk_add_f32 v[182:183], v[190:191], v[182:183]
	v_fmamk_f32 v127, v131, 0xba000000, v127
	v_fmamk_f32 v111, v131, 0xba000000, v111
	v_pk_add_f32 v[182:183], v[16:17], v[182:183]
	v_fmamk_f32 v17, v131, 0xba000000, v129
	v_fmac_f32_e32 v126, 0xba000000, v131
	v_fmamk_f32 v113, v131, 0xba000000, v113
	v_fmac_f32_e32 v110, 0xba000000, v131
	v_mov_b32_e32 v190, v127
	v_mov_b32_e32 v191, v111
	v_fmamk_f32 v16, v131, 0xba000000, v128
	v_fmamk_f32 v112, v131, 0xba000000, v112
	v_mov_b32_e32 v128, v126
	v_mov_b32_e32 v129, v110
	v_pk_mul_f32 v[190:191], v[190:191], v[190:191]
	v_mov_b32_e32 v192, v17
	v_mov_b32_e32 v193, v113
	v_pk_fma_f32 v[128:129], v[128:129], v[128:129], v[190:191]
	v_mov_b32_e32 v190, v16
	v_mov_b32_e32 v191, v112
	v_pk_mul_f32 v[192:193], v[192:193], v[192:193]
	v_fmamk_f32 v95, v131, 0xba000000, v95
	v_pk_fma_f32 v[190:191], v[190:191], v[190:191], v[192:193]
	v_fmamk_f32 v94, v131, 0xba000000, v94
	v_pk_add_f32 v[128:129], v[128:129], v[190:191]
	v_fmamk_f32 v97, v131, 0xba000000, v97
	v_fmac_f32_e32 v96, 0xba000000, v131
	v_pk_add_f32 v[128:129], v[128:129], v[128:129] op_sel_hi:[0,1]
	v_pk_mul_f32 v[190:191], v[96:97], v[96:97]
	v_pk_mul_f32 v[192:193], v[94:95], v[94:95]
	v_fmamk_f32 v86, v131, 0xba000000, v86
	v_pk_mov_b32 v[194:195], v[192:193], v[190:191] op_sel:[1,0]
	v_mov_b32_e32 v193, v191
	v_fmamk_f32 v87, v131, 0xba000000, v87
	v_fmac_f32_e32 v88, 0xba000000, v131
	v_mul_f32_e32 v128, v86, v86
	v_pk_add_f32 v[190:191], v[194:195], v[192:193]
	v_fmamk_f32 v89, v131, 0xba000000, v89
	v_pk_fma_f32 v[192:193], v[86:87], v[86:87], v[128:129] op_sel_hi:[1,1,0]
	v_mul_f32_e32 v128, v88, v88
	v_pk_add_f32 v[190:191], v[190:191], v[190:191] op_sel_hi:[0,1]
	v_pk_fma_f32 v[194:195], v[88:89], v[88:89], v[128:129] op_sel_hi:[1,1,0]
	v_fmamk_f32 v77, v131, 0xba000000, v77
	v_fmamk_f32 v76, v131, 0xba000000, v76
	v_fmamk_f32 v75, v131, 0xba000000, v75
	v_fmac_f32_e32 v74, 0xba000000, v131
	v_mul_f32_e32 v192, v74, v74
	v_mul_f32_e32 v194, v75, v75
	v_mul_f32_e32 v190, v76, v76
	v_mul_f32_e32 v128, v77, v77
	v_pk_add_f32 v[192:193], v[192:193], v[194:195]
	v_pk_add_f32 v[128:129], v[190:191], v[128:129]
	v_fmamk_f32 v55, v131, 0xba000000, v55
	v_pk_add_f32 v[128:129], v[192:193], v[128:129]
	v_fmamk_f32 v54, v131, 0xba000000, v54
	v_fmamk_f32 v57, v131, 0xba000000, v57
	v_fmac_f32_e32 v56, 0xba000000, v131
	v_pk_add_f32 v[128:129], v[128:129], v[128:129] op_sel_hi:[0,1]
	v_pk_mul_f32 v[190:191], v[56:57], v[56:57]
	v_pk_mul_f32 v[192:193], v[54:55], v[54:55]
	v_fmamk_f32 v38, v131, 0xba000000, v38
	v_pk_mov_b32 v[194:195], v[192:193], v[190:191] op_sel:[1,0]
	v_mov_b32_e32 v193, v191
	v_fmamk_f32 v39, v131, 0xba000000, v39
	v_fmac_f32_e32 v40, 0xba000000, v131
	v_mul_f32_e32 v128, v38, v38
	v_pk_add_f32 v[190:191], v[194:195], v[192:193]
	v_fmamk_f32 v41, v131, 0xba000000, v41
	v_pk_fma_f32 v[192:193], v[38:39], v[38:39], v[128:129] op_sel_hi:[1,1,0]
	v_mul_f32_e32 v128, v40, v40
	v_pk_add_f32 v[190:191], v[190:191], v[190:191] op_sel_hi:[0,1]
	v_pk_fma_f32 v[194:195], v[40:41], v[40:41], v[128:129] op_sel_hi:[1,1,0]
	v_fmamk_f32 v33, v131, 0xba000000, v33
	v_fmamk_f32 v32, v131, 0xba000000, v32
	v_fmamk_f32 v31, v131, 0xba000000, v31
	v_fmac_f32_e32 v30, 0xba000000, v131
	v_mul_f32_e32 v192, v30, v30
	v_mul_f32_e32 v194, v31, v31
	v_mul_f32_e32 v190, v32, v32
	v_mul_f32_e32 v128, v33, v33
	v_pk_add_f32 v[192:193], v[192:193], v[194:195]
	v_pk_add_f32 v[128:129], v[190:191], v[128:129]
	s_nop 0
	v_pk_add_f32 v[190:191], v[192:193], v[128:129]
	v_mov_b32_e32 v128, v8
	v_mov_b32_e32 v129, v10
	v_mov_b32_e32 v10, v9
	v_pk_add_f32 v[8:9], v[128:129], v[10:11]
	ds_bpermute_b32 v11, v1, v9
	ds_bpermute_b32 v10, v1, v8
	s_waitcnt lgkmcnt(0)
	v_pk_add_f32 v[8:9], v[8:9], v[10:11]
	ds_bpermute_b32 v11, v181, v9
	ds_bpermute_b32 v10, v181, v8
	s_waitcnt lgkmcnt(0)
	v_pk_add_f32 v[8:9], v[8:9], v[10:11]
	ds_bpermute_b32 v11, v185, v9
	ds_bpermute_b32 v10, v185, v8
	s_waitcnt lgkmcnt(0)
	v_pk_add_f32 v[8:9], v[8:9], v[10:11]
	ds_bpermute_b32 v11, v186, v9
	ds_bpermute_b32 v10, v186, v8
	s_waitcnt lgkmcnt(0)
	v_pk_add_f32 v[8:9], v[8:9], v[10:11]
	ds_bpermute_b32 v11, v187, v9
	ds_bpermute_b32 v10, v187, v8
	s_waitcnt lgkmcnt(0)
	v_pk_add_f32 v[8:9], v[8:9], v[10:11]
	ds_bpermute_b32 v11, v188, v9
	ds_bpermute_b32 v10, v188, v8
	s_waitcnt lgkmcnt(0)
	v_pk_add_f32 v[8:9], v[8:9], v[10:11]
	v_mov_b64_e32 v[10:11], s[8:9]
	v_pk_fma_f32 v[8:9], v[8:9], s[70:71], v[10:11] op_sel_hi:[1,0,0]
	s_nop 0
	v_mul_f32_e32 v128, 0x4b800000, v9
	v_cmp_gt_f32_e64 s[40:41], s73, v9
	v_cmp_gt_f32_e32 vcc, s73, v8
	s_nop 0
	v_cndmask_b32_e64 v9, v9, v128, s[40:41]
	v_rsq_f32_e32 v9, v9
	s_nop 0
	v_mul_f32_e32 v128, 0x45800000, v9
	v_cndmask_b32_e64 v128, v9, v128, s[40:41]
	v_mul_f32_e32 v9, 0x4b800000, v8
	v_cndmask_b32_e32 v8, v8, v9, vcc
	v_rsq_f32_e32 v8, v8
	v_pk_mul_f32 v[114:115], v[114:115], v[128:129] op_sel_hi:[1,0]
	v_pk_mul_f32 v[174:175], v[174:175], v[128:129] op_sel_hi:[1,0]
	v_pk_mul_f32 v[116:117], v[116:117], v[128:129] op_sel_hi:[1,0]
	v_mul_f32_e32 v9, 0x45800000, v8
	v_cndmask_b32_e32 v180, v8, v9, vcc
	v_mov_b32_e32 v8, v190
	v_mov_b32_e32 v9, v182
	v_mov_b32_e32 v182, v191
	v_pk_add_f32 v[8:9], v[8:9], v[182:183]
	ds_bpermute_b32 v183, v1, v9
	ds_bpermute_b32 v182, v1, v8
	v_pk_mul_f32 v[102:103], v[102:103], v[128:129] op_sel_hi:[1,0]
	v_pk_mul_f32 v[106:107], v[106:107], v[180:181] op_sel_hi:[1,0]
	v_pk_mul_f32 v[80:81], v[80:81], v[128:129] op_sel_hi:[1,0]
	v_pk_mul_f32 v[60:61], v[60:61], v[128:129] op_sel_hi:[1,0]
	s_waitcnt lgkmcnt(0)
; __device__ __forceinline__ unsigned cvt_pk_bf16(float lo, float hi) { unsigned r; asm volatile("v_cvt_pk_bf16_f32 %0, %1, %2" : "=v"(r) : "v"(lo), "v"(hi)); return r; }
; template <int MODE, bool COMB, int NR> ...
;     ...
;     for (int o = 1; o < 64; o <<= 1) {
; #pragma unroll
;         for (int i = 0; i < NR; ++i) q[i] += __shfl_xor(q[i], o); }
; #pragma unroll
;     for (int i = 0; i < NR; ++i) rstd[i] = rsqrtf(q[i] * (1.f / D) + LN_EPS);
;     if (MODE != 2) {
; #pragma unroll
;         for (int i = 0; i < NR; ++i) if (lane == i) st[i] = (f32x2){mean[i], rstd[i]};
;     }
; #pragma unroll
;     for (int j = 0; j < 8; ++j) {
;         const f32x4 gg = *(const f32x4*)(g + 4 * lane + 256 * j), bb = *(const f32x4*)(b + 4 * lane + 256 * j);
; #pragma unroll
;         for (int i = 0; i < NR; ++i) {
;             const f32x4 y = v[i][j] * rstd[i] * gg + bb;
;             if (MODE == 2) *(f32x4*)(dstf + (size_t)i * D + 4 * lane + 256 * j) = y;
;             else { u32x2 w; w.x = cvt_pk_bf16(y.x, y.y); w.y = cvt_pk_bf16(y.z, y.w); *(u32x2*)(dstb + (size_t)i * D + 4 * lane + 256 * j) = w; }
;         }
;     }
	v_pk_add_f32 v[8:9], v[8:9], v[182:183]
	ds_bpermute_b32 v183, v181, v9
	ds_bpermute_b32 v182, v181, v8
	v_pk_mul_f32 v[78:79], v[78:79], v[128:129] op_sel_hi:[1,0]
	v_pk_mul_f32 v[42:43], v[42:43], v[128:129] op_sel_hi:[1,0]
	v_pk_mul_f32 v[50:51], v[50:51], v[180:181] op_sel_hi:[1,0]
	v_pk_mul_f32 v[24:25], v[24:25], v[128:129] op_sel_hi:[1,0]
	s_waitcnt lgkmcnt(0)
	v_pk_add_f32 v[8:9], v[8:9], v[182:183]
	ds_bpermute_b32 v183, v185, v9
	ds_bpermute_b32 v182, v185, v8
	v_pk_mul_f32 v[12:13], v[12:13], v[128:129] op_sel_hi:[1,0]
	v_pk_mul_f32 v[22:23], v[22:23], v[128:129] op_sel_hi:[1,0]
	v_pk_mul_f32 v[4:5], v[4:5], v[128:129] op_sel_hi:[1,0]
	v_pk_mul_f32 v[2:3], v[2:3], v[128:129] op_sel_hi:[1,0]
	s_waitcnt lgkmcnt(0)
	v_pk_add_f32 v[8:9], v[8:9], v[182:183]
	ds_bpermute_b32 v183, v186, v9
	ds_bpermute_b32 v182, v186, v8
	s_waitcnt lgkmcnt(0)
	v_pk_add_f32 v[8:9], v[8:9], v[182:183]
	ds_bpermute_b32 v183, v187, v9
	ds_bpermute_b32 v182, v187, v8
	s_waitcnt lgkmcnt(0)
	v_pk_add_f32 v[8:9], v[8:9], v[182:183]
	ds_bpermute_b32 v183, v188, v9
	ds_bpermute_b32 v182, v188, v8
	s_waitcnt lgkmcnt(0)
	v_pk_add_f32 v[8:9], v[8:9], v[182:183]
	s_nop 0
	v_pk_fma_f32 v[8:9], v[8:9], s[70:71], v[10:11] op_sel_hi:[1,0,0]
	s_nop 0
	v_mul_f32_e32 v10, 0x4b800000, v9
	v_cmp_gt_f32_e64 s[40:41], s73, v9
	v_cmp_gt_f32_e32 vcc, s73, v8
	s_nop 0
	v_cndmask_b32_e64 v9, v9, v10, s[40:41]
	v_rsq_f32_e32 v9, v9
	s_nop 0
	v_mul_f32_e32 v10, 0x45800000, v9
	v_cndmask_b32_e64 v182, v9, v10, s[40:41]
	v_mul_f32_e32 v9, 0x4b800000, v8
	v_cndmask_b32_e32 v8, v8, v9, vcc
	v_rsq_f32_e32 v8, v8
	v_pk_mul_f32 v[18:19], v[18:19], v[182:183] op_sel_hi:[1,0]
	v_pk_mul_f32 v[98:99], v[98:99], v[182:183] op_sel_hi:[1,0]
	v_mul_f32_e32 v9, 0x45800000, v8
	v_cndmask_b32_e32 v184, v8, v9, vcc
	ds_read_b128 v[8:11], v132
	ds_read_b128 v[190:193], v132 offset:8192
	v_pk_mul_f32 v[16:17], v[16:17], v[184:185] op_sel_hi:[1,0]
	v_cmp_lt_i32_e32 vcc, s69, v130
	s_or_b64 s[12:13], vcc, s[12:13]
	s_waitcnt lgkmcnt(0)
	v_pk_fma_f32 v[196:197], v[10:11], v[174:175], v[192:193]
	v_pk_fma_f32 v[194:195], v[8:9], v[114:115], v[190:191]
	v_pk_mul_f32 v[114:115], v[118:119], v[180:181] op_sel_hi:[1,0]
	v_pk_mul_f32 v[118:119], v[178:179], v[180:181] op_sel_hi:[1,0]
	global_store_dwordx4 v[152:153], v[194:197], off
	s_nop 1
	v_pk_fma_f32 v[196:197], v[10:11], v[118:119], v[192:193]
	v_pk_fma_f32 v[194:195], v[8:9], v[114:115], v[190:191]
	global_store_dwordx4 v[168:169], v[194:197], off
	v_pk_mul_f32 v[114:115], v[122:123], v[182:183] op_sel_hi:[1,0]
	s_nop 0
	v_pk_fma_f32 v[196:197], v[10:11], v[18:19], v[192:193]
	v_pk_mul_f32 v[18:19], v[126:127], v[184:185] op_sel_hi:[1,0]
	v_pk_fma_f32 v[194:195], v[8:9], v[114:115], v[190:191]
	v_pk_fma_f32 v[10:11], v[10:11], v[16:17], v[192:193]
	v_pk_fma_f32 v[8:9], v[8:9], v[18:19], v[190:191]
	global_store_dwordx4 v[170:171], v[194:197], off
	global_store_dwordx4 v[172:173], v[8:11], off
	s_nop 1
	ds_read_b128 v[8:11], v132 offset:1024
	s_nop 0
	ds_read_b128 v[16:19], v132 offset:9216
	s_waitcnt lgkmcnt(0)
	v_pk_fma_f32 v[114:115], v[8:9], v[102:103], v[16:17]
	v_pk_fma_f32 v[116:117], v[10:11], v[116:117], v[18:19]
	v_pk_mul_f32 v[102:103], v[176:177], v[180:181] op_sel_hi:[1,0]
	global_store_dwordx4 v[152:153], v[114:117], off offset:1024
	s_nop 1
	v_pk_fma_f32 v[114:115], v[8:9], v[106:107], v[16:17]
	v_pk_fma_f32 v[116:117], v[10:11], v[102:103], v[18:19]
	v_pk_mul_f32 v[102:103], v[124:125], v[182:183] op_sel_hi:[1,0]
	global_store_dwordx4 v[168:169], v[114:117], off offset:1024
	s_nop 1
	v_pk_fma_f32 v[114:115], v[8:9], v[98:99], v[16:17]
	v_pk_fma_f32 v[116:117], v[10:11], v[102:103], v[18:19]
	v_pk_mul_f32 v[98:99], v[112:113], v[184:185] op_sel_hi:[1,0]
	v_pk_mul_f32 v[102:103], v[110:111], v[184:185] op_sel_hi:[1,0]
	v_pk_fma_f32 v[10:11], v[10:11], v[98:99], v[18:19]
	v_pk_fma_f32 v[8:9], v[8:9], v[102:103], v[16:17]
	global_store_dwordx4 v[170:171], v[114:117], off offset:1024
	global_store_dwordx4 v[172:173], v[8:11], off offset:1024
	s_nop 1
	ds_read_b128 v[8:11], v132 offset:2048
	s_nop 0
	ds_read_b128 v[16:19], v132 offset:10240
	v_pk_mul_f32 v[98:99], v[104:105], v[128:129] op_sel_hi:[1,0]
	s_waitcnt lgkmcnt(0)
	v_pk_fma_f32 v[104:105], v[80:81], v[10:11], v[18:19]
	v_pk_fma_f32 v[102:103], v[98:99], v[8:9], v[16:17]
	v_pk_mul_f32 v[80:81], v[84:85], v[180:181] op_sel_hi:[1,0]
	v_pk_mul_f32 v[84:85], v[120:121], v[180:181] op_sel_hi:[1,0]
	global_store_dwordx4 v[152:153], v[102:105], off offset:2048
	s_nop 1
	v_pk_fma_f32 v[102:103], v[84:85], v[8:9], v[16:17]
	v_pk_fma_f32 v[104:105], v[80:81], v[10:11], v[18:19]
	v_pk_mul_f32 v[80:81], v[92:93], v[182:183] op_sel_hi:[1,0]
	v_pk_mul_f32 v[84:85], v[100:101], v[182:183] op_sel_hi:[1,0]
	v_pk_fma_f32 v[100:101], v[80:81], v[10:11], v[18:19]
	v_pk_fma_f32 v[98:99], v[84:85], v[8:9], v[16:17]
	v_pk_mul_f32 v[80:81], v[96:97], v[184:185] op_sel_hi:[1,0]
	v_pk_mul_f32 v[84:85], v[94:95], v[184:185] op_sel_hi:[1,0]
	v_pk_fma_f32 v[10:11], v[80:81], v[10:11], v[18:19]
	v_pk_fma_f32 v[8:9], v[84:85], v[8:9], v[16:17]
	global_store_dwordx4 v[168:169], v[102:105], off offset:2048
	global_store_dwordx4 v[170:171], v[98:101], off offset:2048
	global_store_dwordx4 v[172:173], v[8:11], off offset:2048
	s_nop 1
	ds_read_b128 v[8:11], v132 offset:3072
	s_nop 0
	ds_read_b128 v[16:19], v132 offset:11264
	s_waitcnt lgkmcnt(0)
; __device__ __forceinline__ unsigned cvt_pk_bf16(float lo, float hi) { unsigned r; asm volatile("v_cvt_pk_bf16_f32 %0, %1, %2" : "=v"(r) : "v"(lo), "v"(hi)); return r; }
; template <int MODE, bool COMB, int NR> ...
;     ...
; #pragma unroll
;     for (int j = 0; j < 8; ++j) {
;         const f32x4 gg = *(const f32x4*)(g + 4 * lane + 256 * j), bb = *(const f32x4*)(b + 4 * lane + 256 * j);
; #pragma unroll
;         for (int i = 0; i < NR; ++i) {
;             const f32x4 y = v[i][j] * rstd[i] * gg + bb;
;             if (MODE == 2) *(f32x4*)(dstf + (size_t)i * D + 4 * lane + 256 * j) = y;
;             else { u32x2 w; w.x = cvt_pk_bf16(y.x, y.y); w.y = cvt_pk_bf16(y.z, y.w); *(u32x2*)(dstb + (size_t)i * D + 4 * lane + 256 * j) = w; }
;         }
;     }
	v_pk_fma_f32 v[78:79], v[78:79], v[8:9], v[16:17]
	v_pk_fma_f32 v[80:81], v[60:61], v[10:11], v[18:19]
	v_pk_mul_f32 v[60:61], v[68:69], v[180:181] op_sel_hi:[1,0]
	v_pk_mul_f32 v[68:69], v[108:109], v[180:181] op_sel_hi:[1,0]
	global_store_dwordx4 v[152:153], v[78:81], off offset:3072
	v_lshl_add_u64 v[152:153], v[152:153], 0, s[4:5]
	s_nop 0
	v_pk_fma_f32 v[78:79], v[68:69], v[8:9], v[16:17]
	v_pk_fma_f32 v[80:81], v[60:61], v[10:11], v[18:19]
	v_pk_mul_f32 v[60:61], v[72:73], v[182:183] op_sel_hi:[1,0]
	v_pk_mul_f32 v[68:69], v[90:91], v[182:183] op_sel_hi:[1,0]
	global_store_dwordx4 v[168:169], v[78:81], off offset:3072
	s_nop 1
	v_pk_fma_f32 v[78:79], v[68:69], v[8:9], v[16:17]
	v_pk_fma_f32 v[80:81], v[60:61], v[10:11], v[18:19]
	v_pk_mul_f32 v[60:61], v[88:89], v[184:185] op_sel_hi:[1,0]
	v_pk_mul_f32 v[68:69], v[86:87], v[184:185] op_sel_hi:[1,0]
	v_pk_fma_f32 v[10:11], v[60:61], v[10:11], v[18:19]
	v_pk_fma_f32 v[8:9], v[68:69], v[8:9], v[16:17]
	global_store_dwordx4 v[170:171], v[78:81], off offset:3072
	global_store_dwordx4 v[172:173], v[8:11], off offset:3072
	s_nop 1
	ds_read_b128 v[8:11], v132 offset:4096
	s_nop 0
	ds_read_b128 v[16:19], v132 offset:12288
	v_pk_mul_f32 v[60:61], v[58:59], v[128:129] op_sel_hi:[1,0]
	s_waitcnt lgkmcnt(0)
	v_pk_fma_f32 v[58:59], v[42:43], v[8:9], v[16:17]
	v_pk_fma_f32 v[60:61], v[60:61], v[10:11], v[18:19]
	v_pk_mul_f32 v[42:43], v[82:83], v[180:181] op_sel_hi:[1,0]
	global_store_dwordx4 v[160:161], v[58:61], off
	s_nop 1
	v_pk_fma_f32 v[58:59], v[50:51], v[8:9], v[16:17]
	v_pk_fma_f32 v[60:61], v[42:43], v[10:11], v[18:19]
	v_pk_mul_f32 v[42:43], v[70:71], v[182:183] op_sel_hi:[1,0]
	v_pk_mul_f32 v[50:51], v[62:63], v[182:183] op_sel_hi:[1,0]
	global_store_dwordx4 v[162:163], v[58:61], off
	s_nop 1
	v_pk_fma_f32 v[58:59], v[50:51], v[8:9], v[16:17]
	v_pk_fma_f32 v[60:61], v[42:43], v[10:11], v[18:19]
	v_pk_mul_f32 v[42:43], v[76:77], v[184:185] op_sel_hi:[1,0]
	v_pk_mul_f32 v[50:51], v[74:75], v[184:185] op_sel_hi:[1,0]
	v_pk_fma_f32 v[10:11], v[42:43], v[10:11], v[18:19]
	v_pk_fma_f32 v[8:9], v[50:51], v[8:9], v[16:17]
	global_store_dwordx4 v[164:165], v[58:61], off
	global_store_dwordx4 v[166:167], v[8:11], off
	s_nop 1
	ds_read_b128 v[8:11], v132 offset:5120
	s_nop 0
	ds_read_b128 v[16:19], v132 offset:13312
	v_pk_mul_f32 v[42:43], v[44:45], v[128:129] op_sel_hi:[1,0]
	s_waitcnt lgkmcnt(0)
	v_pk_fma_f32 v[44:45], v[24:25], v[10:11], v[18:19]
	v_pk_fma_f32 v[42:43], v[42:43], v[8:9], v[16:17]
	v_pk_mul_f32 v[24:25], v[36:37], v[180:181] op_sel_hi:[1,0]
	v_pk_mul_f32 v[36:37], v[66:67], v[180:181] op_sel_hi:[1,0]
	global_store_dwordx4 v[160:161], v[42:45], off offset:1024
	s_nop 1
	v_pk_fma_f32 v[42:43], v[36:37], v[8:9], v[16:17]
	v_pk_fma_f32 v[44:45], v[24:25], v[10:11], v[18:19]
	v_pk_mul_f32 v[24:25], v[48:49], v[182:183] op_sel_hi:[1,0]
	v_pk_mul_f32 v[36:37], v[64:65], v[182:183] op_sel_hi:[1,0]
	global_store_dwordx4 v[162:163], v[42:45], off offset:1024
	s_nop 1
	v_pk_fma_f32 v[42:43], v[36:37], v[8:9], v[16:17]
	v_pk_fma_f32 v[44:45], v[24:25], v[10:11], v[18:19]
	v_pk_mul_f32 v[24:25], v[56:57], v[184:185] op_sel_hi:[1,0]
	v_pk_mul_f32 v[36:37], v[54:55], v[184:185] op_sel_hi:[1,0]
	v_pk_fma_f32 v[10:11], v[24:25], v[10:11], v[18:19]
	v_pk_fma_f32 v[8:9], v[36:37], v[8:9], v[16:17]
	global_store_dwordx4 v[164:165], v[42:45], off offset:1024
	global_store_dwordx4 v[166:167], v[8:11], off offset:1024
	s_nop 1
	ds_read_b128 v[8:11], v132 offset:6144
	s_nop 0
	ds_read_b128 v[16:19], v132 offset:14336
	s_waitcnt lgkmcnt(0)
	v_pk_fma_f32 v[22:23], v[22:23], v[8:9], v[16:17]
	v_pk_fma_f32 v[24:25], v[12:13], v[10:11], v[18:19]
	v_pk_mul_f32 v[12:13], v[20:21], v[180:181] op_sel_hi:[1,0]
	v_pk_mul_f32 v[20:21], v[52:53], v[180:181] op_sel_hi:[1,0]
	global_store_dwordx4 v[160:161], v[22:25], off offset:2048
	v_pk_fma_f32 v[20:21], v[20:21], v[8:9], v[16:17]
	s_nop 0
	v_pk_fma_f32 v[22:23], v[12:13], v[10:11], v[18:19]
	global_store_dwordx4 v[162:163], v[20:23], off offset:2048
	v_pk_mul_f32 v[12:13], v[28:29], v[182:183] op_sel_hi:[1,0]
	s_nop 0
	v_pk_mul_f32 v[20:21], v[46:47], v[182:183] op_sel_hi:[1,0]
	v_pk_fma_f32 v[22:23], v[12:13], v[10:11], v[18:19]
	v_pk_fma_f32 v[20:21], v[20:21], v[8:9], v[16:17]
	global_store_dwordx4 v[164:165], v[20:23], off offset:2048
	v_pk_mul_f32 v[12:13], v[40:41], v[184:185] op_sel_hi:[1,0]
	s_nop 0
	v_pk_mul_f32 v[20:21], v[38:39], v[184:185] op_sel_hi:[1,0]
	v_pk_fma_f32 v[10:11], v[12:13], v[10:11], v[18:19]
	v_pk_fma_f32 v[8:9], v[20:21], v[8:9], v[16:17]
	global_store_dwordx4 v[166:167], v[8:11], off offset:2048
	s_nop 1
	ds_read_b128 v[8:11], v132 offset:7168
	s_nop 0
	ds_read_b128 v[16:19], v132 offset:15360
	s_waitcnt lgkmcnt(0)
	v_pk_fma_f32 v[2:3], v[2:3], v[8:9], v[16:17]
	v_pk_fma_f32 v[4:5], v[4:5], v[10:11], v[18:19]
	global_store_dwordx4 v[160:161], v[2:5], off offset:3072
	s_nop 1
	v_pk_mul_f32 v[4:5], v[34:35], v[180:181] op_sel_hi:[1,0]
	v_pk_mul_f32 v[2:3], v[6:7], v[180:181] op_sel_hi:[1,0]
	v_pk_fma_f32 v[4:5], v[4:5], v[10:11], v[18:19]
	v_pk_fma_f32 v[2:3], v[2:3], v[8:9], v[16:17]
	global_store_dwordx4 v[162:163], v[2:5], off offset:3072
	s_nop 1
	v_pk_mul_f32 v[4:5], v[26:27], v[182:183] op_sel_hi:[1,0]
	v_pk_mul_f32 v[2:3], v[14:15], v[182:183] op_sel_hi:[1,0]
	v_pk_fma_f32 v[4:5], v[4:5], v[10:11], v[18:19]
	v_pk_fma_f32 v[2:3], v[2:3], v[8:9], v[16:17]
	global_store_dwordx4 v[164:165], v[2:5], off offset:3072
	s_nop 1
	v_pk_mul_f32 v[4:5], v[32:33], v[184:185] op_sel_hi:[1,0]
	v_pk_mul_f32 v[2:3], v[30:31], v[184:185] op_sel_hi:[1,0]
	v_pk_fma_f32 v[4:5], v[4:5], v[10:11], v[18:19]
	v_pk_fma_f32 v[2:3], v[2:3], v[8:9], v[16:17]
	global_store_dwordx4 v[166:167], v[2:5], off offset:3072
	s_andn2_b64 exec, exec, s[12:13]
	s_cbranch_execnz .LBB0_454
